# attention k-loop: hoist loop-invariant LDS address sums into borrowed constant VGPRs (5 fewer VALU per step)
# speedup vs baseline: 1.0066x; 1.0066x over previous
; DEV void attn_item(const Params& p, int item, char* smem) {
;     ...
;   f32x16 o[2][2];
; #pragma unroll
;   for (int dt = 0; dt < 2; dt++)
; #pragma unroll
;     for (int jt = 0; jt < 2; jt++)
; #pragma unroll
;       for (int r = 0; r < 16; r++) o[dt][jt][r] = 0.f;
;   float mrun[2] = {-1e30f, -1e30f}, lrun[2] = {0.f, 0.f};
;   u32x4 rk0, rk1, rv0;
;   const int k0row = tid / 12, k0cc = tid - k0row * 12;
;   const int k1id = 256 + (tid & 127), k1row = k1id / 12, k1cc = k1id - k1row * 12;
;   const bool has_k1 = tid < 128;
;   const int vrow = tid >> 2, vcc = tid & 3;
;   const int ntile = nkeys >> 5;
;   __syncthreads();
;   rk0 = *(const u32x4*)(Kb + (size_t)k0row * 96 + k0cc * 8);
;   rk1 = *(const u32x4*)(Kb + (size_t)k1row * 96 + k1cc * 8);
;   rv0 = *(const u32x4*)(Vb + (size_t)vrow * 8448 + vcc * 8);
;   *(u32x4*)(Ks + k0row * ASTR + k0cc * 8) = rk0;
;   if (has_k1) *(u32x4*)(Ks + k1row * ASTR + k1cc * 8) = rk1;
;   *(uint2*)(Vs + vrow * VSTR + vcc * 8) = make_uint2(rv0[0], rv0[1]);
;   *(uint2*)(Vs + vrow * VSTR + vcc * 8 + 4) = make_uint2(rv0[2], rv0[3]);
;   __syncthreads();
;   if (ntile > 1) {
;     rk0 = *(const u32x4*)(Kb + (size_t)(32 + k0row) * 96 + k0cc * 8);
;     rk1 = *(const u32x4*)(Kb + (size_t)(32 + k1row) * 96 + k1cc * 8);
;     rv0 = *(const u32x4*)(Vb + (size_t)vrow * 8448 + 32 + vcc * 8);
;   }
;     ...
;     if (kt + 1 < ntile) {
;       bf16_t* Kn = Ks + ((kt + 1) & 1) * (32 * ASTR);
;       bf16_t* Vn = Vs + ((kt + 1) & 1) * (64 * VSTR);
;       *(u32x4*)(Kn + k0row * ASTR + k0cc * 8) = rk0;
;       if (has_k1) *(u32x4*)(Kn + k1row * ASTR + k1cc * 8) = rk1;
;       *(uint2*)(Vn + vrow * VSTR + vcc * 8) = make_uint2(rv0[0], rv0[1]);
;       *(uint2*)(Vn + vrow * VSTR + vcc * 8 + 4) = make_uint2(rv0[2], rv0[3]);
;       __syncthreads();
.LBB0_751:
	s_or_b64 exec, exec, s[14:15]
	s_movk_i32 s15, 0x58
	v_mul_lo_u32 v15, v12, s15
	v_lshl_add_u32 v186, v14, 1, v15
	v_add_u32_e32 v14, 0x3400, v186
	s_waitcnt vmcnt(0)
	ds_write2_b64 v14, v[2:3], v[4:5] offset1:1
	v_lshlrev_b64 v[2:3], 1, v[174:175]
	v_lshl_add_u64 v[4:5], v[8:9], 0, v[2:3]
	s_movk_i32 s14, 0x1000
	v_add_co_u32_e32 v4, vcc, s14, v4
	s_waitcnt lgkmcnt(0)
	s_nop 0
	v_addc_co_u32_e32 v5, vcc, 0, v5, vcc
	s_barrier
	global_load_dwordx4 v[160:163], v[6:7], off offset:64
	global_load_dwordx4 v[164:167], v[4:5], off offset:2048
	v_add_u32_e32 v6, 32, v11
	v_mov_b64_e32 v[4:5], s[12:13]
	s_movk_i32 s14, 0xc0
	v_mad_i64_i32 v[4:5], s[12:13], v6, s14, v[4:5]
	v_lshlrev_b64 v[6:7], 1, v[176:177]
	v_lshl_add_u64 v[4:5], v[4:5], 0, v[6:7]
	global_load_dwordx4 v[168:171], v[4:5], off
	v_mad_i64_i32 v[4:5], s[12:13], v11, s14, 0
	s_movk_i32 s12, 0x4200
	s_nop 0
	v_mad_i64_i32 v[8:9], s[12:13], v12, s12, 0
	v_and_b32_e32 v173, 31, v172
	s_movk_i32 s13, 0xd0
	v_mad_u32_u24 v187, v173, s13, v0
	v_lshlrev_b32_e32 v0, 3, v10
	v_mad_u32_u24 v177, v173, s15, v0
	v_and_b32_e32 v0, 3, v172
	v_lshl_add_u64 v[8:9], s[10:11], 0, v[8:9]
	v_lshlrev_b32_e32 v0, 4, v0
	v_lshl_add_u64 v[8:9], v[8:9], 0, v[0:1]
	s_mov_b32 s10, 0x15555556
	v_lshl_add_u64 v[178:179], s[0:1], 0, v[8:9]
	v_mul_hi_u32 v0, v13, s10
	v_mov_b64_e32 v[8:9], s[8:9]
	v_mad_u64_u32 v[8:9], s[10:11], v0, s14, v[8:9]
	v_lshl_add_u64 v[2:3], v[8:9], 0, v[2:3]
	v_lshl_add_u64 v[180:181], s[2:3], 0, v[2:3]
	v_lshl_add_u64 v[2:3], s[8:9], 0, v[4:5]
	v_lshl_add_u64 v[2:3], v[2:3], 0, v[6:7]
	v_mov_b32_e32 v14, v1
	v_mov_b32_e32 v15, v1
	v_lshlrev_b32_e32 v189, 2, v10
	v_lshl_add_u64 v[182:183], s[2:3], 0, v[2:3]
	v_mov_b32_e32 v0, v1
	v_mov_b32_e32 v2, v1
	v_mov_b32_e32 v3, v1
	v_mov_b32_e32 v4, v1
	v_mov_b32_e32 v5, v1
	v_mov_b32_e32 v6, v1
	v_mov_b32_e32 v7, v1
	v_mov_b32_e32 v8, v1
	v_mov_b32_e32 v9, v1
	v_mov_b32_e32 v10, v1
	v_mov_b32_e32 v11, v1
	v_mov_b32_e32 v12, v1
	v_mov_b32_e32 v13, v1
	v_mov_b64_e32 v[62:63], v[14:15]
	v_mov_b64_e32 v[30:31], v[14:15]
	v_mov_b64_e32 v[78:79], v[14:15]
	v_mov_b64_e32 v[46:47], v[14:15]
	s_mov_b32 s12, 0
	v_mul_u32_u24_e32 v190, 0x58, v173
	s_add_i32 s13, s31, 1
	v_mov_b32_e32 v184, 0
	v_mov_b32_e32 v175, 0xf149f2ca
	v_mov_b64_e32 v[60:61], v[12:13]
	v_mov_b64_e32 v[58:59], v[10:11]
	v_mov_b64_e32 v[56:57], v[8:9]
	v_mov_b64_e32 v[54:55], v[6:7]
	v_mov_b64_e32 v[52:53], v[4:5]
	v_mov_b64_e32 v[50:51], v[2:3]
	v_mov_b64_e32 v[48:49], v[0:1]
	v_mov_b64_e32 v[28:29], v[12:13]
	v_mov_b64_e32 v[26:27], v[10:11]
	v_mov_b64_e32 v[24:25], v[8:9]
	v_mov_b64_e32 v[22:23], v[6:7]
	v_mov_b64_e32 v[20:21], v[4:5]
	v_mov_b64_e32 v[18:19], v[2:3]
	v_mov_b64_e32 v[16:17], v[0:1]
	v_mov_b64_e32 v[76:77], v[12:13]
	v_mov_b64_e32 v[74:75], v[10:11]
	v_mov_b64_e32 v[72:73], v[8:9]
	v_mov_b64_e32 v[70:71], v[6:7]
	v_mov_b64_e32 v[68:69], v[4:5]
	v_mov_b64_e32 v[66:67], v[2:3]
	v_mov_b64_e32 v[64:65], v[0:1]
	v_mov_b64_e32 v[44:45], v[12:13]
	v_mov_b64_e32 v[42:43], v[10:11]
	v_mov_b64_e32 v[40:41], v[8:9]
	v_mov_b64_e32 v[38:39], v[6:7]
	v_mov_b64_e32 v[36:37], v[4:5]
	v_mov_b64_e32 v[34:35], v[2:3]
	v_mov_b64_e32 v[32:33], v[0:1]
	v_mov_b32_e32 v185, 0
	v_mov_b32_e32 v175, 0
	v_mov_b32_e32 v14, 0
	v_mov_b32_e32 v212, 0xf149f2ca
	v_mov_b32_e32 v213, 0xf149f2ca
	v_mov_b32_e32 v196, 0
	v_mov_b32_e32 v197, 0
	v_mov_b32_e32 v198, 0
	v_mov_b32_e32 v199, 0
	v_mov_b32_e32 v200, 0
	v_mov_b32_e32 v201, 0
	v_mov_b32_e32 v202, 0
	v_mov_b32_e32 v203, 0
	v_mov_b32_e32 v204, 0
	v_mov_b32_e32 v205, 0
	v_mov_b32_e32 v206, 0
	v_mov_b32_e32 v207, 0
	v_mov_b32_e32 v208, 0
	v_mov_b32_e32 v209, 0
	v_mov_b32_e32 v210, 0
	v_mov_b32_e32 v211, 0
	v_mov_b32_e32 v220, 0
	v_mov_b32_e32 v221, 0
	v_mov_b32_e32 v222, 0
	v_mov_b32_e32 v223, 0
	v_mov_b32_e32 v224, 0
	v_mov_b32_e32 v225, 0
	v_mov_b32_e32 v226, 0
	v_mov_b32_e32 v227, 0
	v_mov_b32_e32 v228, 0
	v_mov_b32_e32 v229, 0
	v_mov_b32_e32 v230, 0
	v_mov_b32_e32 v231, 0
	v_mov_b32_e32 v232, 0
	v_mov_b32_e32 v233, 0
	v_mov_b32_e32 v234, 0
	v_mov_b32_e32 v235, 0
	v_lshlrev_b32_e32 v214, 1, v191
	v_add_u32_e32 v217, 0x3400, v186
	v_add_u32_e32 v219, 0x3000, v177
	v_add_u32_e32 v250, 0x3800, v177
	v_lshl_add_u32 v251, v174, 1, v188
	v_lshl_add_u32 v214, v176, 1, v214
	s_branch .LBB0_753
.LBB0_752:
	s_or_b64 exec, exec, s[8:9]
	v_add_f32_e32 v4, v80, v81
	v_add_f32_e32 v5, v82, v83
	v_add_f32_e32 v4, v4, v5
	v_add_f32_e32 v5, v84, v85
	v_add_f32_e32 v6, v86, v111
	v_add_f32_e32 v5, v5, v6
	v_add_f32_e32 v4, v4, v5
	v_add_f32_e32 v5, v87, v88
	v_add_f32_e32 v6, v89, v90
	v_add_f32_e32 v5, v5, v6
	v_add_f32_e32 v6, v91, v92
	v_add_f32_e32 v2, v2, v3
	v_add_f32_e32 v2, v6, v2
	v_add_f32_e32 v2, v5, v2
	v_add_f32_e32 v2, v4, v2
	v_add_f32_e32 v184, v184, v2
	v_add_f32_e32 v0, v0, v193
	v_add_f32_e32 v2, v194, v239
	v_add_f32_e32 v0, v0, v2
	v_add_f32_e32 v2, v100, v101
	v_add_f32_e32 v3, v102, v240
	v_add_f32_e32 v2, v2, v3
	v_add_f32_e32 v0, v0, v2
	v_add_f32_e32 v2, v103, v104
	v_add_f32_e32 v3, v105, v106
	v_add_f32_e32 v2, v2, v3
	v_add_f32_e32 v3, v107, v108
	v_add_f32_e32 v4, v109, v110
	v_add_f32_e32 v3, v3, v4
	v_add_f32_e32 v2, v2, v3
	s_mul_i32 s8, s14, 0x1600
	v_add_f32_e32 v0, v0, v2
	v_add_f32_e32 v14, v14, v0
	v_add_u32_e32 v0, s8, v217
	ds_write2_b64 v0, v[160:161], v[162:163] offset1:1
	s_waitcnt lgkmcnt(0)
	s_barrier
	global_load_dwordx4 v[168:171], v[182:183], off
	global_load_dwordx4 v[164:167], v[180:181], off
	global_load_dwordx4 v[160:163], v[178:179], off
	s_mov_b64 s[8:9], 0x1800
	v_lshl_add_u64 v[178:179], v[178:179], 0, 64
	v_lshl_add_u64 v[180:181], v[180:181], 0, s[8:9]
	v_lshl_add_u64 v[182:183], v[182:183], 0, s[8:9]
	s_cmp_eq_u32 s13, s12
	s_cbranch_scc1 .LBB0_759

; DEV void attn_item(const Params& p, int item, char* smem) {
;     ...
;     for (int jt = 0; jt < 2; jt++) {
;       float m0 = fmaxf(fmaxf(s[jt][0], s[jt][1]), fmaxf(s[jt][2], s[jt][3]));
;       float m1 = fmaxf(fmaxf(s[jt][4], s[jt][5]), fmaxf(s[jt][6], s[jt][7]));
;       float m2 = fmaxf(fmaxf(s[jt][8], s[jt][9]), fmaxf(s[jt][10], s[jt][11]));
;       float m3 = fmaxf(fmaxf(s[jt][12], s[jt][13]), fmaxf(s[jt][14], s[jt][15]));
;       const float mx = fmaxf(fmaxf(m0, m1), fmaxf(m2, m3));
;       if (__any(mx > mrun[jt])) {
;         const float mxa = fmaxf(mx, __shfl_xor(mx, 32));
;         const float mnew = fmaxf(mrun[jt], mxa);
;         const float alpha = __builtin_amdgcn_exp2f(mrun[jt] - mnew);
;         mrun[jt] = mnew;
;         lrun[jt] *= alpha;
; #pragma unroll
;         for (int dt = 0; dt < 2; dt++)
; #pragma unroll
;           for (int r = 0; r < 16; r++) o[dt][jt][r] *= alpha;
;       }
;       const float mcur = mrun[jt];
;       float pv[16];
; #pragma unroll
;       for (int r = 0; r < 16; r++) pv[r] = __builtin_amdgcn_exp2f(s[jt][r] - mcur);
;       lrun[jt] += (((pv[0] + pv[1]) + (pv[2] + pv[3])) + ((pv[4] + pv[5]) + (pv[6] + pv[7]))) +
;                   (((pv[8] + pv[9]) + (pv[10] + pv[11])) + ((pv[12] + pv[13]) + (pv[14] + pv[15])));
;       bf16x8 pf[2];
; #pragma unroll
;       for (int ss = 0; ss < 2; ss++) {
;         uint4 u; u.x = pack2(pv[8 * ss + 0], pv[8 * ss + 1]); u.y = pack2(pv[8 * ss + 2], pv[8 * ss + 3]);
;         u.z = pack2(pv[8 * ss + 4], pv[8 * ss + 5]); u.w = pack2(pv[8 * ss + 6], pv[8 * ss + 7]);
;         pf[ss] = __builtin_bit_cast(bf16x8, u);
;       }
; #pragma unroll
;       for (int dt = 0; dt < 2; dt++)
; #pragma unroll
;         for (int ss = 0; ss < 2; ss++) {
;           uint2 lo = *(const uint2*)(Vc + (dt * 32 + c31) * VSTR + 16 * ss + 4 * hf);
;           uint2 hi = *(const uint2*)(Vc + (dt * 32 + c31) * VSTR + 16 * ss + 8 + 4 * hf);
;           uint4 u; u.x = lo.x; u.y = lo.y; u.z = hi.x; u.w = hi.y;
;           o[dt][jt] = mfma32(__builtin_bit_cast(bf16x8, u), pf[ss], o[dt][jt]);
;         }
;     }
;     if (kt + 1 < ntile) {
;       bf16_t* Kn = Ks + ((kt + 1) & 1) * (32 * ASTR);
;       bf16_t* Vn = Vs + ((kt + 1) & 1) * (64 * VSTR);
;       *(u32x4*)(Kn + k0row * ASTR + k0cc * 8) = rk0;
;       if (has_k1) *(u32x4*)(Kn + k1row * ASTR + k1cc * 8) = rk1;
.LBB0_755:
	v_exp_f32_e32 v193, v97
	v_exp_f32_e32 v194, v98
	v_exp_f32_e32 v239, v99
	v_exp_f32_e32 v100, v100
	v_exp_f32_e32 v101, v101
	v_exp_f32_e32 v102, v102
	v_exp_f32_e32 v240, v103
	v_exp_f32_e32 v103, v104
	v_exp_f32_e32 v104, v105
	v_exp_f32_e32 v105, v106
	v_exp_f32_e32 v106, v107
	s_mulk_i32 s11, 0x1600
	v_exp_f32_e32 v107, v108
	v_exp_f32_e32 v108, v109
	v_add_u32_e32 v6, s11, v219
	v_exp_f32_e32 v109, v110
	v_add_u32_e32 v15, s11, v250
	v_exp_f32_e32 v110, v111
	ds_read2_b64 v[2:5], v6 offset0:128 offset1:130
	ds_read2_b64 v[6:9], v6 offset0:132 offset1:134
	ds_read2_b64 v[10:13], v15 offset0:224 offset1:226
	v_exp_f32_e32 v0, v96
	v_cvt_pk_bf16_f32 v97, v194, v239
	v_cvt_pk_bf16_f32 v98, v100, v101
	v_cvt_pk_bf16_f32 v99, v102, v240
	v_cvt_pk_bf16_f32 v96, v0, v193
	v_max3_f32 v111, v80, v81, v82
	v_cvt_pk_bf16_f32 v242, v103, v104
	s_waitcnt lgkmcnt(2)
	v_mfma_f32_32x32x16_bf16 v[32:47], v[2:5], v[96:99], v[32:47]
	v_cvt_pk_bf16_f32 v243, v105, v106
	v_cvt_pk_bf16_f32 v244, v107, v108
	v_cvt_pk_bf16_f32 v245, v109, v110
	v_max3_f32 v192, v83, v84, v85
	v_max3_f32 v236, v86, v87, v88
	v_max3_f32 v237, v89, v90, v91
	v_max3_f32 v238, v92, v93, v94
	s_waitcnt lgkmcnt(0)
	v_mfma_f32_32x32x16_bf16 v[16:31], v[10:13], v[96:99], v[16:31]
	ds_read2_b64 v[96:99], v15 offset0:228 offset1:230
	v_max3_f32 v15, v111, v192, v95
	v_max3_f32 v236, v236, v237, v238
	v_mfma_f32_32x32x16_bf16 v[32:47], v[6:9], v[242:245], v[32:47]
	s_nop 1
	v_max_f32_e32 v15, v15, v236
	s_waitcnt lgkmcnt(0)
	v_mfma_f32_32x32x16_bf16 v[16:31], v[96:99], v[242:245], v[16:31]
	v_cmp_gt_f32_e32 vcc, v15, v213
	s_cbranch_vccz .LBB0_757
	v_mbcnt_hi_u32_b32 v111, -1, v215
	v_and_b32_e32 v236, 64, v111
	v_xor_b32_e32 v192, 32, v111
	v_add_u32_e32 v236, 64, v236
	v_cmp_lt_i32_e32 vcc, v192, v236
	s_nop 1
	v_cndmask_b32_e32 v111, v111, v192, vcc
	v_lshlrev_b32_e32 v111, 2, v111
	ds_bpermute_b32 v111, v111, v15
	s_waitcnt lgkmcnt(0)
	v_max_f32_e32 v111, v15, v111
	v_exp_f32_e64 v192, -v111
	v_add_f32_e32 v175, v175, v111
	v_mov_b32_e32 v213, 0x41000000
	v_sub_f32_e32 v80, v80, v111
	v_sub_f32_e32 v81, v81, v111
	v_sub_f32_e32 v82, v82, v111
	v_sub_f32_e32 v83, v83, v111
	v_sub_f32_e32 v84, v84, v111
	v_sub_f32_e32 v85, v85, v111
	v_sub_f32_e32 v86, v86, v111
	v_sub_f32_e32 v87, v87, v111
	v_sub_f32_e32 v88, v88, v111
	v_sub_f32_e32 v89, v89, v111
	v_sub_f32_e32 v90, v90, v111
	v_sub_f32_e32 v91, v91, v111
	v_sub_f32_e32 v92, v92, v111
	v_sub_f32_e32 v93, v93, v111
	v_sub_f32_e32 v94, v94, v111
	v_sub_f32_e32 v95, v95, v111
	v_sub_f32_e32 v220, v220, v111
	v_sub_f32_e32 v221, v221, v111
	v_sub_f32_e32 v222, v222, v111
	v_sub_f32_e32 v223, v223, v111
	v_sub_f32_e32 v224, v224, v111
	v_sub_f32_e32 v225, v225, v111
	v_sub_f32_e32 v226, v226, v111
	v_sub_f32_e32 v227, v227, v111
	v_sub_f32_e32 v228, v228, v111
	v_sub_f32_e32 v229, v229, v111
	v_sub_f32_e32 v230, v230, v111
	v_sub_f32_e32 v231, v231, v111
	v_sub_f32_e32 v232, v232, v111
	v_sub_f32_e32 v233, v233, v111
	v_sub_f32_e32 v234, v234, v111
	v_sub_f32_e32 v235, v235, v111
	v_mul_f32_e32 v184, v184, v192
	v_pk_mul_f32 v[78:79], v[78:79], v[192:193] op_sel_hi:[1,0]
	v_pk_mul_f32 v[76:77], v[76:77], v[192:193] op_sel_hi:[1,0]
	v_pk_mul_f32 v[74:75], v[74:75], v[192:193] op_sel_hi:[1,0]
	v_pk_mul_f32 v[72:73], v[72:73], v[192:193] op_sel_hi:[1,0]
	v_pk_mul_f32 v[70:71], v[70:71], v[192:193] op_sel_hi:[1,0]
	v_pk_mul_f32 v[68:69], v[68:69], v[192:193] op_sel_hi:[1,0]
	v_pk_mul_f32 v[66:67], v[66:67], v[192:193] op_sel_hi:[1,0]
	v_pk_mul_f32 v[64:65], v[64:65], v[192:193] op_sel_hi:[1,0]
	v_pk_mul_f32 v[62:63], v[62:63], v[192:193] op_sel_hi:[1,0]
	v_pk_mul_f32 v[60:61], v[60:61], v[192:193] op_sel_hi:[1,0]
	v_pk_mul_f32 v[58:59], v[58:59], v[192:193] op_sel_hi:[1,0]
	v_pk_mul_f32 v[56:57], v[56:57], v[192:193] op_sel_hi:[1,0]
	v_pk_mul_f32 v[54:55], v[54:55], v[192:193] op_sel_hi:[1,0]
	v_pk_mul_f32 v[52:53], v[52:53], v[192:193] op_sel_hi:[1,0]
	v_pk_mul_f32 v[50:51], v[50:51], v[192:193] op_sel_hi:[1,0]
	v_pk_mul_f32 v[48:49], v[48:49], v[192:193] op_sel_hi:[1,0]
.LBB0_757:
	v_exp_f32_e32 v80, v80
	v_exp_f32_e32 v81, v81
	v_exp_f32_e32 v82, v82
	v_exp_f32_e32 v83, v83
	v_exp_f32_e32 v84, v84
	v_exp_f32_e32 v85, v85
	v_exp_f32_e32 v86, v86
	v_exp_f32_e32 v111, v87
	v_exp_f32_e32 v87, v88
	v_exp_f32_e32 v88, v89
	v_exp_f32_e32 v89, v90
	v_cvt_pk_bf16_f32 v242, v80, v81
	v_cvt_pk_bf16_f32 v243, v82, v83
	v_cvt_pk_bf16_f32 v244, v84, v85
	v_cvt_pk_bf16_f32 v245, v86, v111
	v_exp_f32_e32 v90, v91
	v_exp_f32_e32 v91, v92
	v_mfma_f32_32x32x16_bf16 v[64:79], v[2:5], v[242:245], v[64:79]
	v_exp_f32_e32 v92, v93
	v_exp_f32_e32 v2, v94
	v_exp_f32_e32 v3, v95
	v_mfma_f32_32x32x16_bf16 v[48:63], v[10:13], v[242:245], v[48:63]
	v_cvt_pk_bf16_f32 v246, v87, v88
	v_cvt_pk_bf16_f32 v247, v89, v90
	v_cvt_pk_bf16_f32 v248, v91, v92
	v_cvt_pk_bf16_f32 v249, v2, v3
	s_add_i32 s12, s12, 1
	s_and_b32 s14, s12, 1
	s_mul_i32 s15, s14, 0x1a00
	v_mfma_f32_32x32x16_bf16 v[64:79], v[6:9], v[246:249], v[64:79]
	v_add_u32_e32 v4, s15, v214
	s_waitcnt vmcnt(0)
	ds_write_b128 v4, v[168:171]
	v_mfma_f32_32x32x16_bf16 v[48:63], v[96:99], v[246:249], v[48:63]
	s_and_saveexec_b64 s[8:9], s[38:39]
	s_cbranch_execz .LBB0_752
	v_add_u32_e32 v4, s15, v251
	ds_write_b128 v4, v[164:167]
	s_branch .LBB0_752

; DEV void phase_attn(const Params& p, char* smem) {
;   for (int item = blockIdx.x; item < 512 + 16; item += gridDim.x) attn_item(p, item, smem);
; }
.LBB0_770:
	s_setprio 0
	v_mov_b32_e32 v214, 0xbab64f3b
	v_xor_b32_e32 v217, 1, v216
	v_xor_b32_e32 v219, 2, v216
	v_mov_b32_e32 v250, 0x42000000
	v_mov_b32_e32 v251, 0x42800000
	v_mov_b32_e32 v196, 0x3ba10414
	v_mov_b32_e32 v197, 0x13c00
	v_mov_b32_e32 v198, 0x13c04
	v_mov_b32_e32 v199, 1
	v_mov_b32_e32 v200, 0x13b40
	v_mov_b32_e32 v201, 0x13b50
	v_mov_b32_e32 v202, 0x13b60
	v_mov_b32_e32 v203, 0x13b70
	v_mov_b32_e32 v204, 0x13b80
	v_mov_b32_e32 v205, 0x13b90
	v_mov_b32_e32 v206, 0x13ba0
	v_mov_b32_e32 v207, 0x13bb0
	v_mov_b32_e32 v208, 0x13bc0
	v_mov_b32_e32 v209, 0x13bd0
	v_mov_b32_e32 v210, 0x13be0
	v_mov_b32_e32 v211, 0x358637bd
	v_mov_b32_e32 v212, 0x8300000
	v_mov_b32_e32 v213, 0x7fc00000
	v_mov_b32_e32 v222, 0xb9c68948
	v_mov_b32_e32 v223, 0x7f800000
	v_mov_b32_e32 v224, 0xe300000
	v_mov_b32_e32 v225, 0x41b17218
	v_mov_b32_e32 v226, -12
	v_mov_b32_e32 v227, 0x9800
	v_mov_b32_e32 v228, 0x6700000
	v_mov_b32_e32 v229, 0xc300000
	v_xor_b32_e32 v220, 4, v216
	v_xor_b32_e32 v221, 8, v216
	v_not_b32_e32 v230, 63
	v_not_b32_e32 v231, 31
	v_readlane_b32 s30, v253, 11
	v_readlane_b32 s28, v254, 0
	v_readlane_b32 s31, v253, 12
	s_movk_i32 s19, 0x880
	s_movk_i32 s23, 0x3fff
	s_movk_i32 s21, 0x2000
	v_readlane_b32 s29, v254, 1
